# gemm256 K-loops: s_setprio 1 over the fragment ds_read / ds_write / global_load feed, s_setprio 0 over each 8-MFMA group
# baseline (speedup 1.0000x reference)
; template <class Toff, class Setup, class Epi>
; DI void gemm256_stream(int tiles_per_xcd, int K, long ais, long akcs, long bis, Toff toff, Setup setup, Epi epi, char* smem) {
;     ...
;   const int nk = K >> 6;
;   __syncthreads();
;   G256_GLOAD(Ac, Bc, 0)
;   G256_SSTORE(0)
;   G256_GLOAD(Ac, Bc, 1)
;   __syncthreads();
;   while (true) {
;     const int qn = q + nj;
;     const bool has_next = qn < tiles_per_xcd;
;     if (has_next) setup(xcd, qn, An, Bn);
;     for (int kt = 0; kt < nk; ++kt) {
;       const int s = kt & 1;
;       const bool have1 = (kt + 1 < nk) || has_next;
;       const bool in_cur = (kt + 2 < nk);
;       const bool have2 = in_cur || (has_next && kt + 2 == nk);
;       const u16* Ap2 = in_cur ? Ac : An;
;       const u16* Bp2 = in_cur ? Bc : Bn;
;       const int kt2 = in_cur ? kt + 2 : kt + 2 - nk;
;       const char* base = smem + s * STAGE;
;       G256_KSTEP(0, ra0, rb0)
;       G256_KSTEP(1, ra1, rb1)
;       G256_KSTEP(2, ra2, rb2)
;       G256_KSTEP(3, ra3, rb3)
;       __syncthreads();
;     }
.LBB0_109:
	s_and_b32 s6, s4, 0x10000
	s_add_i32 s5, s6, 0
	v_add_u32_e32 v0, s5, v216
	v_add3_u32 v174, v0, v220, v221
	v_add3_u32 v0, v0, v222, v221
	s_xor_b32 s6, s6, 0x10000
	s_setprio 1
	ds_read_b128 v[162:165], v174
	ds_read_b128 v[166:169], v174 offset:4096
	ds_read_b128 v[178:181], v174 offset:8192
	ds_read_b128 v[182:185], v174 offset:12288
	ds_read_b128 v[192:195], v0 offset:32768
	ds_read_b128 v[248:251], v0 offset:36864
	v_add_u32_e32 v0, s6, v215
	v_lshl_add_u64 v[174:175], v[172:173], 0, s[0:1]
	s_waitcnt vmcnt(7)
	ds_write_b128 v0, v[142:145]
	s_waitcnt vmcnt(6)
	ds_write_b128 v0, v[158:161] offset:32768
	v_add_co_u32_e32 v142, vcc, s7, v174
	v_lshl_add_u64 v[176:177], v[170:171], 0, s[0:1]
	s_nop 0
	v_addc_co_u32_e32 v143, vcc, 0, v175, vcc
	s_mov_b32 s6, 0x3820000
	v_add_co_u32_e32 v158, vcc, s6, v176
	global_load_dwordx4 v[142:145], v[142:143], off offset:3328
	s_nop 0
	v_addc_co_u32_e32 v159, vcc, 0, v177, vcc
	global_load_dwordx4 v[158:161], v[158:159], off offset:256
	s_waitcnt lgkmcnt(3)
	s_setprio 0
	v_mfma_f32_32x32x16_bf16 v[114:129], v[162:165], v[192:195], v[114:129]
	s_mov_b32 s6, 0x3840000
	v_mfma_f32_32x32x16_bf16 v[82:97], v[166:169], v[192:195], v[82:97]
	v_mfma_f32_32x32x16_bf16 v[50:65], v[178:181], v[192:195], v[50:65]
	v_mfma_f32_32x32x16_bf16 v[18:33], v[182:185], v[192:195], v[18:33]
	v_add_u32_e32 v192, s5, v217
	v_add3_u32 v247, v192, v222, v221
	s_waitcnt lgkmcnt(2)
	v_mfma_f32_32x32x16_bf16 v[2:17], v[182:185], v[248:251], v[2:17]
	v_add3_u32 v182, v192, v220, v221
	v_mfma_f32_32x32x16_bf16 v[98:113], v[162:165], v[248:251], v[98:113]
	v_mfma_f32_32x32x16_bf16 v[66:81], v[166:169], v[248:251], v[66:81]
	v_mfma_f32_32x32x16_bf16 v[34:49], v[178:181], v[248:251], v[34:49]
	s_setprio 1
	ds_read_b128 v[162:165], v182
	ds_read_b128 v[166:169], v182 offset:4096
	ds_read_b128 v[178:181], v182 offset:8192
	ds_read_b128 v[182:185], v182 offset:12288
	ds_read_b128 v[192:195], v247 offset:32768
	ds_read_b128 v[248:251], v247 offset:36864
	s_waitcnt vmcnt(7)
	ds_write_b128 v0, v[138:141] offset:8192
	s_waitcnt vmcnt(6)
	ds_write_b128 v0, v[154:157] offset:40960
	v_add_co_u32_e32 v138, vcc, s8, v174
	s_nop 1
	v_addc_co_u32_e32 v139, vcc, 0, v175, vcc
	v_add_co_u32_e32 v154, vcc, s6, v176
	global_load_dwordx4 v[138:141], v[138:139], off offset:3328
	s_nop 0
	v_addc_co_u32_e32 v155, vcc, 0, v177, vcc
	global_load_dwordx4 v[154:157], v[154:155], off offset:256
	s_waitcnt lgkmcnt(3)
	s_setprio 0
	v_mfma_f32_32x32x16_bf16 v[114:129], v[162:165], v[192:195], v[114:129]
	s_mov_b32 s6, 0x3860000
	v_mfma_f32_32x32x16_bf16 v[82:97], v[166:169], v[192:195], v[82:97]
	v_mfma_f32_32x32x16_bf16 v[50:65], v[178:181], v[192:195], v[50:65]
	v_mfma_f32_32x32x16_bf16 v[18:33], v[182:185], v[192:195], v[18:33]
	v_add_u32_e32 v192, s5, v218
	v_add3_u32 v247, v192, v222, v221
	s_waitcnt lgkmcnt(2)
	v_mfma_f32_32x32x16_bf16 v[2:17], v[182:185], v[248:251], v[2:17]
	v_add3_u32 v182, v192, v220, v221
	v_mfma_f32_32x32x16_bf16 v[98:113], v[162:165], v[248:251], v[98:113]
	v_mfma_f32_32x32x16_bf16 v[66:81], v[166:169], v[248:251], v[66:81]
	v_mfma_f32_32x32x16_bf16 v[34:49], v[178:181], v[248:251], v[34:49]
	s_setprio 1
	ds_read_b128 v[162:165], v182
	ds_read_b128 v[166:169], v182 offset:4096
	ds_read_b128 v[178:181], v182 offset:8192
	ds_read_b128 v[182:185], v182 offset:12288
	ds_read_b128 v[192:195], v247 offset:32768
	ds_read_b128 v[248:251], v247 offset:36864
	s_waitcnt vmcnt(7)
	ds_write_b128 v0, v[134:137] offset:16384
	s_waitcnt vmcnt(6)
	ds_write_b128 v0, v[150:153] offset:49152
	v_add_co_u32_e32 v134, vcc, s9, v174
	s_nop 1
	v_addc_co_u32_e32 v135, vcc, 0, v175, vcc
	v_add_co_u32_e32 v150, vcc, s6, v176
	global_load_dwordx4 v[134:137], v[134:135], off offset:3328
	s_nop 0
	v_addc_co_u32_e32 v151, vcc, 0, v177, vcc
	global_load_dwordx4 v[150:153], v[150:151], off offset:256
	s_waitcnt lgkmcnt(3)
	s_setprio 0
	v_mfma_f32_32x32x16_bf16 v[82:97], v[166:169], v[192:195], v[82:97]
	s_waitcnt lgkmcnt(2)
	v_mfma_f32_32x32x16_bf16 v[66:81], v[166:169], v[248:251], v[66:81]
	v_add_u32_e32 v166, s5, v219
	s_mov_b32 s5, 0x3880000
	v_mfma_f32_32x32x16_bf16 v[114:129], v[162:165], v[192:195], v[114:129]
	v_mfma_f32_32x32x16_bf16 v[98:113], v[162:165], v[248:251], v[98:113]
	v_add3_u32 v162, v166, v220, v221
	v_add3_u32 v166, v166, v222, v221
	v_mfma_f32_32x32x16_bf16 v[50:65], v[178:181], v[192:195], v[50:65]
	v_mfma_f32_32x32x16_bf16 v[34:49], v[178:181], v[248:251], v[34:49]
	v_mfma_f32_32x32x16_bf16 v[18:33], v[182:185], v[192:195], v[18:33]
	v_mfma_f32_32x32x16_bf16 v[2:17], v[182:185], v[248:251], v[2:17]
	s_setprio 1
	ds_read_b128 v[178:181], v162
	ds_read_b128 v[182:185], v162 offset:4096
	ds_read_b128 v[192:195], v162 offset:8192
	ds_read_b128 v[162:165], v162 offset:12288
	ds_read_b128 v[248:251], v166 offset:32768
	ds_read_b128 v[166:169], v166 offset:36864
	s_waitcnt vmcnt(7)
	ds_write_b128 v0, v[130:133] offset:24576
	s_waitcnt vmcnt(6)
	ds_write_b128 v0, v[146:149] offset:57344
	v_add_co_u32_e32 v130, vcc, s10, v174
	s_nop 1
	v_addc_co_u32_e32 v131, vcc, 0, v175, vcc
	v_add_co_u32_e32 v146, vcc, s5, v176
	global_load_dwordx4 v[130:133], v[130:131], off offset:3328
	s_nop 0
	v_addc_co_u32_e32 v147, vcc, 0, v177, vcc
	global_load_dwordx4 v[146:149], v[146:147], off offset:256
	s_waitcnt lgkmcnt(3)
	s_setprio 0
	v_mfma_f32_32x32x16_bf16 v[114:129], v[178:181], v[248:251], v[114:129]
	s_add_u32 s0, s0, 0x80
	s_addc_u32 s1, s1, 0
	s_add_i32 s4, s4, 0x10000
	s_cmpk_eq_i32 s0, 0x700
	s_waitcnt lgkmcnt(0)
	s_barrier
	v_mfma_f32_32x32x16_bf16 v[98:113], v[178:181], v[166:169], v[98:113]
	v_mfma_f32_32x32x16_bf16 v[82:97], v[182:185], v[248:251], v[82:97]
	v_mfma_f32_32x32x16_bf16 v[66:81], v[182:185], v[166:169], v[66:81]
	v_mfma_f32_32x32x16_bf16 v[50:65], v[192:195], v[248:251], v[50:65]
	v_mfma_f32_32x32x16_bf16 v[34:49], v[192:195], v[166:169], v[34:49]
	v_mfma_f32_32x32x16_bf16 v[18:33], v[162:165], v[248:251], v[18:33]
	v_mfma_f32_32x32x16_bf16 v[2:17], v[162:165], v[166:169], v[2:17]
	s_cbranch_scc0 .LBB0_109
	s_setprio 0
	s_add_i32 s7, s20, s58
	s_lshl_b32 s0, s7, 18
	s_and_b32 s0, s0, 0x3c0000
	s_lshl_b32 s1, s7, 14
	ds_read_b128 v[182:185], v231
	ds_read_b128 v[178:181], v231 offset:4096
	ds_read_b128 v[166:169], v231 offset:8192
	ds_read_b128 v[162:165], v231 offset:12288
	ds_read_b128 v[170:173], v232 offset:32768
	ds_read_b128 v[174:177], v232 offset:36864
	s_or_b32 s0, s0, s83
	s_and_b32 s4, s1, 0x40000
	s_cmp_lt_u32 s7, 32
	s_cselect_b64 s[10:11], -1, 0
	s_lshl_b32 s1, s0, 1
	s_add_u32 s8, s12, s1
	s_addc_u32 s9, s13, 0
	s_lshl_b32 s1, s4, 1
	s_add_u32 s22, s18, s1
	s_addc_u32 s23, s19, 0
	s_cmp_gt_u32 s7, 31
	v_lshl_add_u64 v[192:193], s[22:23], 0, v[186:187]
	v_lshl_add_u64 v[194:195], s[8:9], 0, v[186:187]
	s_waitcnt vmcnt(7)
	ds_write_b128 v223, v[142:145]
	s_waitcnt vmcnt(6)
	ds_write_b128 v224, v[158:161]
	s_cbranch_scc1 .LBB0_112
	global_load_dwordx4 v[142:145], v[194:195], off
	global_load_dwordx4 v[158:161], v[192:193], off

; template <class Toff, class Setup, class Epi>
; DI void gemm256_stream(int tiles_per_xcd, int K, long ais, long akcs, long bis, Toff toff, Setup setup, Epi epi, char* smem) {
;     ...
;   const int nk = K >> 6;
;   __syncthreads();
;   G256_GLOAD(Ac, Bc, 0)
;   G256_SSTORE(0)
;   G256_GLOAD(Ac, Bc, 1)
;   __syncthreads();
;   while (true) {
;     const int qn = q + nj;
;     const bool has_next = qn < tiles_per_xcd;
;     if (has_next) setup(xcd, qn, An, Bn);
;     for (int kt = 0; kt < nk; ++kt) {
;       const int s = kt & 1;
;       const bool have1 = (kt + 1 < nk) || has_next;
;       const bool in_cur = (kt + 2 < nk);
;       const bool have2 = in_cur || (has_next && kt + 2 == nk);
;       const u16* Ap2 = in_cur ? Ac : An;
;       const u16* Bp2 = in_cur ? Bc : Bn;
;       const int kt2 = in_cur ? kt + 2 : kt + 2 - nk;
;       const char* base = smem + s * STAGE;
;       G256_KSTEP(0, ra0, rb0)
;       G256_KSTEP(1, ra1, rb1)
;       G256_KSTEP(2, ra2, rb2)
;       G256_KSTEP(3, ra3, rb3)
;       __syncthreads();
;     }
.LBB0_144:
	s_and_b32 s10, s7, 0x10000
	s_add_i32 s6, s10, 0
	v_add_u32_e32 v0, s6, v216
	v_add3_u32 v174, v0, v220, v221
	v_add3_u32 v0, v0, v222, v221
	s_xor_b32 s10, s10, 0x10000
	s_setprio 1
	ds_read_b128 v[162:165], v174
	ds_read_b128 v[166:169], v174 offset:4096
	ds_read_b128 v[178:181], v174 offset:8192
	ds_read_b128 v[182:185], v174 offset:12288
	ds_read_b128 v[192:195], v0 offset:32768
	ds_read_b128 v[248:251], v0 offset:36864
	v_add_u32_e32 v0, s10, v215
	v_lshl_add_u64 v[174:175], v[172:173], 0, s[8:9]
	s_waitcnt vmcnt(7)
	ds_write_b128 v0, v[142:145]
	s_waitcnt vmcnt(6)
	ds_write_b128 v0, v[158:161] offset:32768
	v_add_co_u32_e32 v142, vcc, s11, v174
	v_lshl_add_u64 v[176:177], v[170:171], 0, s[8:9]
	s_nop 0
	v_addc_co_u32_e32 v143, vcc, 0, v175, vcc
	s_mov_b32 s10, 0x2980000
	v_add_co_u32_e32 v158, vcc, s10, v176
	global_load_dwordx4 v[142:145], v[142:143], off offset:3328
	s_nop 0
	v_addc_co_u32_e32 v159, vcc, 0, v177, vcc
	global_load_dwordx4 v[158:161], v[158:159], off offset:256
	s_waitcnt lgkmcnt(3)
	s_setprio 0
	v_mfma_f32_32x32x16_bf16 v[114:129], v[162:165], v[192:195], v[114:129]
	s_mov_b32 s10, 0x29a0000
	v_mfma_f32_32x32x16_bf16 v[82:97], v[166:169], v[192:195], v[82:97]
	v_mfma_f32_32x32x16_bf16 v[50:65], v[178:181], v[192:195], v[50:65]
	v_mfma_f32_32x32x16_bf16 v[18:33], v[182:185], v[192:195], v[18:33]
	v_add_u32_e32 v192, s6, v217
	v_add3_u32 v247, v192, v222, v221
	s_waitcnt lgkmcnt(2)
	v_mfma_f32_32x32x16_bf16 v[2:17], v[182:185], v[248:251], v[2:17]
	v_add3_u32 v182, v192, v220, v221
	v_mfma_f32_32x32x16_bf16 v[98:113], v[162:165], v[248:251], v[98:113]
	v_mfma_f32_32x32x16_bf16 v[66:81], v[166:169], v[248:251], v[66:81]
	v_mfma_f32_32x32x16_bf16 v[34:49], v[178:181], v[248:251], v[34:49]
	s_setprio 1
	ds_read_b128 v[162:165], v182
	ds_read_b128 v[166:169], v182 offset:4096
	ds_read_b128 v[178:181], v182 offset:8192
	ds_read_b128 v[182:185], v182 offset:12288
	ds_read_b128 v[192:195], v247 offset:32768
	ds_read_b128 v[248:251], v247 offset:36864
	s_waitcnt vmcnt(7)
	ds_write_b128 v0, v[138:141] offset:8192
	s_waitcnt vmcnt(6)
	ds_write_b128 v0, v[154:157] offset:40960
	v_add_co_u32_e32 v138, vcc, s12, v174
	s_nop 1
	v_addc_co_u32_e32 v139, vcc, 0, v175, vcc
	v_add_co_u32_e32 v154, vcc, s10, v176
	global_load_dwordx4 v[138:141], v[138:139], off offset:3328
	s_nop 0
	v_addc_co_u32_e32 v155, vcc, 0, v177, vcc
	global_load_dwordx4 v[154:157], v[154:155], off offset:256
	s_waitcnt lgkmcnt(3)
	s_setprio 0
	v_mfma_f32_32x32x16_bf16 v[114:129], v[162:165], v[192:195], v[114:129]
	s_mov_b32 s10, 0x29c0000
	v_mfma_f32_32x32x16_bf16 v[82:97], v[166:169], v[192:195], v[82:97]
	v_mfma_f32_32x32x16_bf16 v[50:65], v[178:181], v[192:195], v[50:65]
	v_mfma_f32_32x32x16_bf16 v[18:33], v[182:185], v[192:195], v[18:33]
	v_add_u32_e32 v192, s6, v218
	v_add3_u32 v247, v192, v222, v221
	s_waitcnt lgkmcnt(2)
	v_mfma_f32_32x32x16_bf16 v[2:17], v[182:185], v[248:251], v[2:17]
	v_add3_u32 v182, v192, v220, v221
	v_mfma_f32_32x32x16_bf16 v[98:113], v[162:165], v[248:251], v[98:113]
	v_mfma_f32_32x32x16_bf16 v[66:81], v[166:169], v[248:251], v[66:81]
	v_mfma_f32_32x32x16_bf16 v[34:49], v[178:181], v[248:251], v[34:49]
	s_setprio 1
	ds_read_b128 v[162:165], v182
	ds_read_b128 v[166:169], v182 offset:4096
	ds_read_b128 v[178:181], v182 offset:8192
	ds_read_b128 v[182:185], v182 offset:12288
	ds_read_b128 v[192:195], v247 offset:32768
	ds_read_b128 v[248:251], v247 offset:36864
	s_waitcnt vmcnt(7)
	ds_write_b128 v0, v[134:137] offset:16384
	s_waitcnt vmcnt(6)
	ds_write_b128 v0, v[150:153] offset:49152
	v_add_co_u32_e32 v134, vcc, s13, v174
	s_nop 1
	v_addc_co_u32_e32 v135, vcc, 0, v175, vcc
	v_add_co_u32_e32 v150, vcc, s10, v176
	global_load_dwordx4 v[134:137], v[134:135], off offset:3328
	s_nop 0
	v_addc_co_u32_e32 v151, vcc, 0, v177, vcc
	global_load_dwordx4 v[150:153], v[150:151], off offset:256
	s_waitcnt lgkmcnt(3)
	s_setprio 0
	v_mfma_f32_32x32x16_bf16 v[82:97], v[166:169], v[192:195], v[82:97]
	s_waitcnt lgkmcnt(2)
	v_mfma_f32_32x32x16_bf16 v[66:81], v[166:169], v[248:251], v[66:81]
	v_add_u32_e32 v166, s6, v219
	s_mov_b32 s6, 0x29e0000
	v_mfma_f32_32x32x16_bf16 v[114:129], v[162:165], v[192:195], v[114:129]
	v_mfma_f32_32x32x16_bf16 v[98:113], v[162:165], v[248:251], v[98:113]
	v_add3_u32 v162, v166, v220, v221
	v_add3_u32 v166, v166, v222, v221
	v_mfma_f32_32x32x16_bf16 v[50:65], v[178:181], v[192:195], v[50:65]
	v_mfma_f32_32x32x16_bf16 v[34:49], v[178:181], v[248:251], v[34:49]
	v_mfma_f32_32x32x16_bf16 v[18:33], v[182:185], v[192:195], v[18:33]
	v_mfma_f32_32x32x16_bf16 v[2:17], v[182:185], v[248:251], v[2:17]
	s_setprio 1
	ds_read_b128 v[178:181], v162
	ds_read_b128 v[182:185], v162 offset:4096
	ds_read_b128 v[192:195], v162 offset:8192
	ds_read_b128 v[162:165], v162 offset:12288
	ds_read_b128 v[248:251], v166 offset:32768
	ds_read_b128 v[166:169], v166 offset:36864
	s_waitcnt vmcnt(7)
	ds_write_b128 v0, v[130:133] offset:24576
	s_waitcnt vmcnt(6)
	ds_write_b128 v0, v[146:149] offset:57344
	v_add_co_u32_e32 v130, vcc, s16, v174
	s_nop 1
	v_addc_co_u32_e32 v131, vcc, 0, v175, vcc
	v_add_co_u32_e32 v146, vcc, s6, v176
	global_load_dwordx4 v[130:133], v[130:131], off offset:3328
	s_nop 0
	v_addc_co_u32_e32 v147, vcc, 0, v177, vcc
	global_load_dwordx4 v[146:149], v[146:147], off offset:256
	s_waitcnt lgkmcnt(3)
	s_setprio 0
	v_mfma_f32_32x32x16_bf16 v[114:129], v[178:181], v[248:251], v[114:129]
	s_add_u32 s8, s8, 0x80
	s_addc_u32 s9, s9, 0
	s_add_i32 s7, s7, 0x10000
	s_cmpk_eq_i32 s8, 0x700
	s_waitcnt lgkmcnt(0)
	s_barrier
	v_mfma_f32_32x32x16_bf16 v[98:113], v[178:181], v[166:169], v[98:113]
	v_mfma_f32_32x32x16_bf16 v[82:97], v[182:185], v[248:251], v[82:97]
	v_mfma_f32_32x32x16_bf16 v[66:81], v[182:185], v[166:169], v[66:81]
	v_mfma_f32_32x32x16_bf16 v[50:65], v[192:195], v[248:251], v[50:65]
	v_mfma_f32_32x32x16_bf16 v[34:49], v[192:195], v[166:169], v[34:49]
	v_mfma_f32_32x32x16_bf16 v[18:33], v[162:165], v[248:251], v[18:33]
	v_mfma_f32_32x32x16_bf16 v[2:17], v[162:165], v[166:169], v[2:17]
	s_cbranch_scc0 .LBB0_144
	s_setprio 0
	s_add_i32 s22, s23, s58
	s_lshl_b32 s6, s22, 15
	s_and_b32 s10, s6, 0x3c0000
	s_lshl_b32 s6, s22, 18
	s_and_b32 s6, s6, 0x1c0000
	s_or_b32 s12, s6, s65
	ds_read_b128 v[182:185], v231
	ds_read_b128 v[178:181], v231 offset:4096
	ds_read_b128 v[166:169], v231 offset:8192
	ds_read_b128 v[162:165], v231 offset:12288
	ds_read_b128 v[170:173], v232 offset:32768
	ds_read_b128 v[174:177], v232 offset:36864
	s_lshl_b32 s6, s12, 1
	s_add_u32 s6, s18, s6
	s_addc_u32 s7, s19, 0
	s_cmpk_lt_u32 s22, 0x80
	s_cselect_b64 s[16:17], -1, 0
	s_lshl_b32 s8, s10, 1
	s_add_u32 s8, s20, s8
	s_addc_u32 s9, s21, 0
	s_cmpk_gt_u32 s22, 0x7f
	v_lshl_add_u64 v[192:193], s[8:9], 0, v[186:187]
	v_lshl_add_u64 v[194:195], s[6:7], 0, v[186:187]
	s_waitcnt vmcnt(7)
	ds_write_b128 v223, v[142:145]
	s_waitcnt vmcnt(6)
	ds_write_b128 v224, v[158:161]
	s_cbranch_scc1 .LBB0_147
	global_load_dwordx4 v[142:145], v[194:195], off
	global_load_dwordx4 v[158:161], v[192:193], off

; template <class Toff, class Setup, class Epi>
; DI void gemm256_stream(int tiles_per_xcd, int K, long ais, long akcs, long bis, Toff toff, Setup setup, Epi epi, char* smem) {
;     ...
;   const int nk = K >> 6;
;   __syncthreads();
;   G256_GLOAD(Ac, Bc, 0)
;   G256_SSTORE(0)
;   G256_GLOAD(Ac, Bc, 1)
;   __syncthreads();
;   while (true) {
;     const int qn = q + nj;
;     const bool has_next = qn < tiles_per_xcd;
;     if (has_next) setup(xcd, qn, An, Bn);
;     for (int kt = 0; kt < nk; ++kt) {
;       const int s = kt & 1;
;       const bool have1 = (kt + 1 < nk) || has_next;
;       const bool in_cur = (kt + 2 < nk);
;       const bool have2 = in_cur || (has_next && kt + 2 == nk);
;       const u16* Ap2 = in_cur ? Ac : An;
;       const u16* Bp2 = in_cur ? Bc : Bn;
;       const int kt2 = in_cur ? kt + 2 : kt + 2 - nk;
;       const char* base = smem + s * STAGE;
;       G256_KSTEP(0, ra0, rb0)
;       G256_KSTEP(1, ra1, rb1)
;       G256_KSTEP(2, ra2, rb2)
;       G256_KSTEP(3, ra3, rb3)
;       __syncthreads();
;     }
.LBB0_613:
	s_and_b32 s8, s7, 0x10000
	s_add_i32 s6, s8, 0
	v_add_u32_e32 v0, s6, v216
	v_add3_u32 v174, v0, v220, v221
	v_add3_u32 v0, v0, v222, v221
	s_xor_b32 s8, s8, 0x10000
	s_setprio 1
	ds_read_b128 v[162:165], v174
	ds_read_b128 v[166:169], v174 offset:4096
	ds_read_b128 v[178:181], v174 offset:8192
	ds_read_b128 v[182:185], v174 offset:12288
	ds_read_b128 v[192:195], v0 offset:32768
	ds_read_b128 v[248:251], v0 offset:36864
	v_add_u32_e32 v0, s8, v215
	v_lshl_add_u64 v[174:175], v[172:173], 0, s[0:1]
	s_waitcnt vmcnt(7)
	ds_write_b128 v0, v[142:145]
	s_waitcnt vmcnt(6)
	ds_write_b128 v0, v[158:161] offset:32768
	v_add_co_u32_e32 v142, vcc, s9, v174
	v_lshl_add_u64 v[176:177], v[170:171], 0, s[0:1]
	s_nop 0
	v_addc_co_u32_e32 v143, vcc, 0, v175, vcc
	s_mov_b32 s8, 0x2100000
	v_add_co_u32_e32 v158, vcc, s8, v176
	global_load_dwordx4 v[142:145], v[142:143], off offset:3328
	s_nop 0
	v_addc_co_u32_e32 v159, vcc, 0, v177, vcc
	global_load_dwordx4 v[158:161], v[158:159], off offset:256
	s_waitcnt lgkmcnt(3)
	s_setprio 0
	v_mfma_f32_32x32x16_bf16 v[114:129], v[162:165], v[192:195], v[114:129]
	s_mov_b32 s8, 0x2120000
	v_mfma_f32_32x32x16_bf16 v[82:97], v[166:169], v[192:195], v[82:97]
	v_mfma_f32_32x32x16_bf16 v[50:65], v[178:181], v[192:195], v[50:65]
	v_mfma_f32_32x32x16_bf16 v[18:33], v[182:185], v[192:195], v[18:33]
	v_add_u32_e32 v192, s6, v217
	v_add3_u32 v247, v192, v222, v221
	s_waitcnt lgkmcnt(2)
	v_mfma_f32_32x32x16_bf16 v[2:17], v[182:185], v[248:251], v[2:17]
	v_add3_u32 v182, v192, v220, v221
	v_mfma_f32_32x32x16_bf16 v[98:113], v[162:165], v[248:251], v[98:113]
	v_mfma_f32_32x32x16_bf16 v[66:81], v[166:169], v[248:251], v[66:81]
	v_mfma_f32_32x32x16_bf16 v[34:49], v[178:181], v[248:251], v[34:49]
	s_setprio 1
	ds_read_b128 v[162:165], v182
	ds_read_b128 v[166:169], v182 offset:4096
	ds_read_b128 v[178:181], v182 offset:8192
	ds_read_b128 v[182:185], v182 offset:12288
	ds_read_b128 v[192:195], v247 offset:32768
	ds_read_b128 v[248:251], v247 offset:36864
	s_waitcnt vmcnt(7)
	ds_write_b128 v0, v[138:141] offset:8192
	s_waitcnt vmcnt(6)
	ds_write_b128 v0, v[154:157] offset:40960
	v_add_co_u32_e32 v138, vcc, s10, v174
	s_nop 1
	v_addc_co_u32_e32 v139, vcc, 0, v175, vcc
	v_add_co_u32_e32 v154, vcc, s8, v176
	global_load_dwordx4 v[138:141], v[138:139], off offset:3328
	s_nop 0
	v_addc_co_u32_e32 v155, vcc, 0, v177, vcc
	global_load_dwordx4 v[154:157], v[154:155], off offset:256
	s_waitcnt lgkmcnt(3)
	s_setprio 0
	v_mfma_f32_32x32x16_bf16 v[114:129], v[162:165], v[192:195], v[114:129]
	s_mov_b32 s8, 0x2140000
	v_mfma_f32_32x32x16_bf16 v[82:97], v[166:169], v[192:195], v[82:97]
	v_mfma_f32_32x32x16_bf16 v[50:65], v[178:181], v[192:195], v[50:65]
	v_mfma_f32_32x32x16_bf16 v[18:33], v[182:185], v[192:195], v[18:33]
	v_add_u32_e32 v192, s6, v218
	v_add3_u32 v247, v192, v222, v221
	s_waitcnt lgkmcnt(2)
	v_mfma_f32_32x32x16_bf16 v[2:17], v[182:185], v[248:251], v[2:17]
	v_add3_u32 v182, v192, v220, v221
	v_mfma_f32_32x32x16_bf16 v[98:113], v[162:165], v[248:251], v[98:113]
	v_mfma_f32_32x32x16_bf16 v[66:81], v[166:169], v[248:251], v[66:81]
	v_mfma_f32_32x32x16_bf16 v[34:49], v[178:181], v[248:251], v[34:49]
	s_setprio 1
	ds_read_b128 v[162:165], v182
	ds_read_b128 v[166:169], v182 offset:4096
	ds_read_b128 v[178:181], v182 offset:8192
	ds_read_b128 v[182:185], v182 offset:12288
	ds_read_b128 v[192:195], v247 offset:32768
	ds_read_b128 v[248:251], v247 offset:36864
	s_waitcnt vmcnt(7)
	ds_write_b128 v0, v[134:137] offset:16384
	s_waitcnt vmcnt(6)
	ds_write_b128 v0, v[150:153] offset:49152
	v_add_co_u32_e32 v134, vcc, s11, v174
	s_nop 1
	v_addc_co_u32_e32 v135, vcc, 0, v175, vcc
	v_add_co_u32_e32 v150, vcc, s8, v176
	global_load_dwordx4 v[134:137], v[134:135], off offset:3328
	s_nop 0
	v_addc_co_u32_e32 v151, vcc, 0, v177, vcc
	global_load_dwordx4 v[150:153], v[150:151], off offset:256
	s_waitcnt lgkmcnt(3)
	s_setprio 0
	v_mfma_f32_32x32x16_bf16 v[82:97], v[166:169], v[192:195], v[82:97]
	s_waitcnt lgkmcnt(2)
	v_mfma_f32_32x32x16_bf16 v[66:81], v[166:169], v[248:251], v[66:81]
	v_add_u32_e32 v166, s6, v219
	s_mov_b32 s6, 0x2160000
	v_mfma_f32_32x32x16_bf16 v[114:129], v[162:165], v[192:195], v[114:129]
	v_mfma_f32_32x32x16_bf16 v[98:113], v[162:165], v[248:251], v[98:113]
	v_add3_u32 v162, v166, v220, v221
	v_add3_u32 v166, v166, v222, v221
	v_mfma_f32_32x32x16_bf16 v[50:65], v[178:181], v[192:195], v[50:65]
	v_mfma_f32_32x32x16_bf16 v[34:49], v[178:181], v[248:251], v[34:49]
	v_mfma_f32_32x32x16_bf16 v[18:33], v[182:185], v[192:195], v[18:33]
	v_mfma_f32_32x32x16_bf16 v[2:17], v[182:185], v[248:251], v[2:17]
	s_setprio 1
	ds_read_b128 v[178:181], v162
	ds_read_b128 v[182:185], v162 offset:4096
	ds_read_b128 v[192:195], v162 offset:8192
	ds_read_b128 v[162:165], v162 offset:12288
	ds_read_b128 v[248:251], v166 offset:32768
	ds_read_b128 v[166:169], v166 offset:36864
	s_waitcnt vmcnt(7)
	ds_write_b128 v0, v[130:133] offset:24576
	s_waitcnt vmcnt(6)
	ds_write_b128 v0, v[146:149] offset:57344
	v_add_co_u32_e32 v130, vcc, s17, v174
	s_nop 1
	v_addc_co_u32_e32 v131, vcc, 0, v175, vcc
	v_add_co_u32_e32 v146, vcc, s6, v176
	global_load_dwordx4 v[130:133], v[130:131], off offset:3328
	s_nop 0
	v_addc_co_u32_e32 v147, vcc, 0, v177, vcc
	global_load_dwordx4 v[146:149], v[146:147], off offset:256
	s_waitcnt lgkmcnt(3)
	s_setprio 0
	v_mfma_f32_32x32x16_bf16 v[114:129], v[178:181], v[248:251], v[114:129]
	s_add_u32 s0, s0, 0x80
	s_addc_u32 s1, s1, 0
	s_add_i32 s7, s7, 0x10000
	s_cmpk_eq_i32 s0, 0x700
	s_waitcnt lgkmcnt(0)
	s_barrier
	v_mfma_f32_32x32x16_bf16 v[98:113], v[178:181], v[166:169], v[98:113]
	v_mfma_f32_32x32x16_bf16 v[82:97], v[182:185], v[248:251], v[82:97]
	v_mfma_f32_32x32x16_bf16 v[66:81], v[182:185], v[166:169], v[66:81]
	v_mfma_f32_32x32x16_bf16 v[50:65], v[192:195], v[248:251], v[50:65]
	v_mfma_f32_32x32x16_bf16 v[34:49], v[192:195], v[166:169], v[34:49]
	v_mfma_f32_32x32x16_bf16 v[18:33], v[162:165], v[248:251], v[18:33]
	v_mfma_f32_32x32x16_bf16 v[2:17], v[162:165], v[166:169], v[2:17]
	s_cbranch_scc0 .LBB0_613
	s_setprio 0
	s_add_i32 s29, s16, s58
	s_lshl_b32 s0, s29, 15
	s_and_b32 s92, s0, 0x7c0000
	s_lshl_b32 s0, s29, 18
	s_and_b32 s0, s0, 0x1c0000
	s_or_b32 s76, s0, s65
	ds_read_b128 v[182:185], v231
	ds_read_b128 v[178:181], v231 offset:4096
	ds_read_b128 v[166:169], v231 offset:8192
	ds_read_b128 v[162:165], v231 offset:12288
	ds_read_b128 v[170:173], v232 offset:32768
	ds_read_b128 v[174:177], v232 offset:36864
	s_lshl_b32 s0, s76, 1
	s_add_u32 s0, s18, s0
	s_addc_u32 s1, s19, 0
	s_cmpk_lt_u32 s29, 0x88
	s_cselect_b64 s[86:87], -1, 0
	s_lshl_b32 s6, s92, 1
	s_add_u32 s6, s20, s6
	s_addc_u32 s7, s21, 0
	s_cmpk_gt_u32 s29, 0x87
	v_lshl_add_u64 v[192:193], s[6:7], 0, v[186:187]
	v_lshl_add_u64 v[194:195], s[0:1], 0, v[186:187]
	s_waitcnt vmcnt(7)
	ds_write_b128 v223, v[142:145]
	s_waitcnt vmcnt(6)
	ds_write_b128 v224, v[158:161]
	s_cbranch_scc1 .LBB0_616
	global_load_dwordx4 v[142:145], v[194:195], off
	global_load_dwordx4 v[158:161], v[192:193], off

; template <class Toff, class Setup, class Epi>
; DI void gemm256_stream(int tiles_per_xcd, int K, long ais, long akcs, long bis, Toff toff, Setup setup, Epi epi, char* smem) {
;     ...
;   const int nk = K >> 6;
;   __syncthreads();
;   G256_GLOAD(Ac, Bc, 0)
;   G256_SSTORE(0)
;   G256_GLOAD(Ac, Bc, 1)
;   __syncthreads();
;   while (true) {
;     const int qn = q + nj;
;     const bool has_next = qn < tiles_per_xcd;
;     if (has_next) setup(xcd, qn, An, Bn);
;     for (int kt = 0; kt < nk; ++kt) {
;       const int s = kt & 1;
;       const bool have1 = (kt + 1 < nk) || has_next;
;       const bool in_cur = (kt + 2 < nk);
;       const bool have2 = in_cur || (has_next && kt + 2 == nk);
;       const u16* Ap2 = in_cur ? Ac : An;
;       const u16* Bp2 = in_cur ? Bc : Bn;
;       const int kt2 = in_cur ? kt + 2 : kt + 2 - nk;
;       const char* base = smem + s * STAGE;
;       G256_KSTEP(0, ra0, rb0)
;       G256_KSTEP(1, ra1, rb1)
;       G256_KSTEP(2, ra2, rb2)
;       G256_KSTEP(3, ra3, rb3)
;       __syncthreads();
;     }
.LBB0_825:
	s_and_b32 s49, s7, 0x10000
	s_add_i32 s6, s49, 0
	v_add_u32_e32 v178, s6, v192
	s_xor_b32 s49, s49, 0x10000
	v_add3_u32 v174, v178, v215, v216
	v_add3_u32 v182, v178, v217, v216
	v_add_u32_e32 v188, s49, v0
	s_setprio 1
	ds_read_b128 v[162:165], v174
	ds_read_b128 v[166:169], v174 offset:4096
	ds_read_b128 v[170:173], v174 offset:8192
	ds_read_b128 v[174:177], v174 offset:12288
	ds_read_b128 v[178:181], v182 offset:32768
	ds_read_b128 v[182:185], v182 offset:36864
	s_waitcnt vmcnt(7)
	ds_write_b128 v188, v[146:149]
	s_waitcnt vmcnt(6)
	ds_write_b128 v188, v[158:161] offset:32768
	v_lshl_add_u64 v[146:147], s[8:9], 0, v[186:187]
	v_lshl_add_u64 v[158:159], s[22:23], 0, v[186:187]
	global_load_dwordx4 v[146:149], v[146:147], off
	s_add_i32 s35, s35, 1
	global_load_dwordx4 v[158:161], v[158:159], off
	s_waitcnt lgkmcnt(3)
	s_setprio 0
	v_mfma_f32_32x32x16_bf16 v[114:129], v[162:165], v[178:181], v[114:129]
	v_mfma_f32_32x32x16_bf16 v[82:97], v[166:169], v[178:181], v[82:97]
	v_mfma_f32_32x32x16_bf16 v[50:65], v[170:173], v[178:181], v[50:65]
	v_mfma_f32_32x32x16_bf16 v[18:33], v[174:177], v[178:181], v[18:33]
	v_add_u32_e32 v178, s6, v193
	s_waitcnt lgkmcnt(2)
	v_mfma_f32_32x32x16_bf16 v[98:113], v[162:165], v[182:185], v[98:113]
	v_mfma_f32_32x32x16_bf16 v[66:81], v[166:169], v[182:185], v[66:81]
	v_mfma_f32_32x32x16_bf16 v[34:49], v[170:173], v[182:185], v[34:49]
	v_mfma_f32_32x32x16_bf16 v[2:17], v[174:177], v[182:185], v[2:17]
	v_add3_u32 v174, v178, v215, v216
	v_add3_u32 v182, v178, v217, v216
	s_setprio 1
	ds_read_b128 v[162:165], v174
	ds_read_b128 v[166:169], v174 offset:4096
	ds_read_b128 v[170:173], v174 offset:8192
	ds_read_b128 v[174:177], v174 offset:12288
	ds_read_b128 v[178:181], v182 offset:32768
	ds_read_b128 v[182:185], v182 offset:36864
	s_waitcnt vmcnt(7)
	ds_write_b128 v188, v[138:141] offset:8192
	s_waitcnt vmcnt(6)
	ds_write_b128 v188, v[154:157] offset:40960
	v_lshl_add_u64 v[138:139], s[20:21], 0, v[186:187]
	v_lshl_add_u64 v[154:155], s[28:29], 0, v[186:187]
	global_load_dwordx4 v[138:141], v[138:139], off
	s_nop 0
	global_load_dwordx4 v[154:157], v[154:155], off
	s_waitcnt lgkmcnt(3)
	s_setprio 0
	v_mfma_f32_32x32x16_bf16 v[114:129], v[162:165], v[178:181], v[114:129]
	v_mfma_f32_32x32x16_bf16 v[82:97], v[166:169], v[178:181], v[82:97]
	v_mfma_f32_32x32x16_bf16 v[50:65], v[170:173], v[178:181], v[50:65]
	v_mfma_f32_32x32x16_bf16 v[18:33], v[174:177], v[178:181], v[18:33]
	v_add_u32_e32 v178, s6, v194
	s_waitcnt lgkmcnt(2)
	v_mfma_f32_32x32x16_bf16 v[98:113], v[162:165], v[182:185], v[98:113]
	v_mfma_f32_32x32x16_bf16 v[66:81], v[166:169], v[182:185], v[66:81]
	v_mfma_f32_32x32x16_bf16 v[34:49], v[170:173], v[182:185], v[34:49]
	v_mfma_f32_32x32x16_bf16 v[2:17], v[174:177], v[182:185], v[2:17]
	v_add3_u32 v174, v178, v215, v216
	v_add3_u32 v182, v178, v217, v216
	s_setprio 1
	ds_read_b128 v[162:165], v174
	ds_read_b128 v[166:169], v174 offset:4096
	ds_read_b128 v[170:173], v174 offset:8192
	ds_read_b128 v[174:177], v174 offset:12288
	ds_read_b128 v[178:181], v182 offset:32768
	ds_read_b128 v[182:185], v182 offset:36864
	s_waitcnt vmcnt(7)
	ds_write_b128 v188, v[134:137] offset:16384
	s_waitcnt vmcnt(6)
	ds_write_b128 v188, v[150:153] offset:49152
	v_lshl_add_u64 v[134:135], s[18:19], 0, v[186:187]
	v_lshl_add_u64 v[150:151], s[26:27], 0, v[186:187]
	global_load_dwordx4 v[134:137], v[134:135], off
	s_nop 0
	global_load_dwordx4 v[150:153], v[150:151], off
	s_waitcnt lgkmcnt(3)
	s_setprio 0
	v_mfma_f32_32x32x16_bf16 v[82:97], v[166:169], v[178:181], v[82:97]
	s_waitcnt lgkmcnt(2)
	v_mfma_f32_32x32x16_bf16 v[66:81], v[166:169], v[182:185], v[66:81]
	v_add_u32_e32 v166, s6, v195
	v_mfma_f32_32x32x16_bf16 v[114:129], v[162:165], v[178:181], v[114:129]
	v_mfma_f32_32x32x16_bf16 v[98:113], v[162:165], v[182:185], v[98:113]
	v_add3_u32 v162, v166, v215, v216
	v_add3_u32 v166, v166, v217, v216
	v_mfma_f32_32x32x16_bf16 v[50:65], v[170:173], v[178:181], v[50:65]
	v_mfma_f32_32x32x16_bf16 v[34:49], v[170:173], v[182:185], v[34:49]
	v_mfma_f32_32x32x16_bf16 v[18:33], v[174:177], v[178:181], v[18:33]
	v_mfma_f32_32x32x16_bf16 v[2:17], v[174:177], v[182:185], v[2:17]
	s_setprio 1
	ds_read_b128 v[178:181], v162
	ds_read_b128 v[182:185], v162 offset:4096
	ds_read_b128 v[174:177], v162 offset:8192
	ds_read_b128 v[162:165], v162 offset:12288
	ds_read_b128 v[170:173], v166 offset:32768
	ds_read_b128 v[166:169], v166 offset:36864
	s_waitcnt vmcnt(7)
	ds_write_b128 v188, v[130:133] offset:24576
	s_waitcnt vmcnt(6)
	ds_write_b128 v188, v[142:145] offset:57344
	v_lshl_add_u64 v[130:131], s[16:17], 0, v[186:187]
	v_lshl_add_u64 v[142:143], s[24:25], 0, v[186:187]
	global_load_dwordx4 v[130:133], v[130:131], off
	s_nop 0
	global_load_dwordx4 v[142:145], v[142:143], off
	s_add_i32 s7, s7, 0x10000
	s_add_u32 s16, s16, 0x80
	s_addc_u32 s17, s17, 0
	s_add_u32 s18, s18, 0x80
	s_addc_u32 s19, s19, 0
	s_add_u32 s20, s20, 0x80
	s_addc_u32 s21, s21, 0
	s_add_u32 s8, s8, 0x80
	s_addc_u32 s9, s9, 0
	s_add_u32 s24, s24, 0x80
	s_waitcnt lgkmcnt(3)
	s_setprio 0
	v_mfma_f32_32x32x16_bf16 v[114:129], v[178:181], v[170:173], v[114:129]
	s_addc_u32 s25, s25, 0
	s_add_u32 s26, s26, 0x80
	s_addc_u32 s27, s27, 0
	s_add_u32 s28, s28, 0x80
	s_addc_u32 s29, s29, 0
	s_add_u32 s22, s22, 0x80
	s_addc_u32 s23, s23, 0
	s_waitcnt lgkmcnt(2)
	v_mfma_f32_32x32x16_bf16 v[98:113], v[178:181], v[166:169], v[98:113]
	s_cmp_eq_u32 s44, s35
	s_waitcnt lgkmcnt(0)
	s_barrier
	v_mfma_f32_32x32x16_bf16 v[82:97], v[182:185], v[170:173], v[82:97]
	v_mfma_f32_32x32x16_bf16 v[66:81], v[182:185], v[166:169], v[66:81]
	v_mfma_f32_32x32x16_bf16 v[50:65], v[174:177], v[170:173], v[50:65]
	v_mfma_f32_32x32x16_bf16 v[34:49], v[174:177], v[166:169], v[34:49]
	v_mfma_f32_32x32x16_bf16 v[18:33], v[162:165], v[170:173], v[18:33]
	v_mfma_f32_32x32x16_bf16 v[2:17], v[162:165], v[166:169], v[2:17]
	s_cbranch_scc0 .LBB0_825
	s_setprio 0
	s_lshl_b32 s6, s44, 16
	s_and_b32 s7, s6, 0x10000
	s_add_i32 s6, s7, 0
	v_add_u32_e32 v170, s6, v192
	v_add3_u32 v162, v170, v215, v216
	ds_read_b128 v[182:185], v162
	ds_read_b128 v[178:181], v162 offset:4096
	ds_read_b128 v[166:169], v162 offset:8192
	ds_read_b128 v[162:165], v162 offset:12288
	v_add3_u32 v174, v170, v217, v216
	ds_read_b128 v[170:173], v174 offset:32768
	ds_read_b128 v[174:177], v174 offset:36864
	s_xor_b32 s7, s7, 0x10000
	v_cndmask_b32_e64 v188, 0, 1, s[0:1]
	v_add_u32_e32 v226, s7, v0
	v_cmp_ne_u32_e64 s[8:9], 1, v188
	s_andn2_b64 vcc, exec, s[0:1]
	v_lshl_add_u64 v[190:191], s[84:85], 0, v[186:187]
	v_lshl_add_u64 v[188:189], s[92:93], 0, v[186:187]
	s_waitcnt vmcnt(7)
	ds_write_b128 v226, v[146:149]
	s_waitcnt vmcnt(6)
	ds_write_b128 v226, v[158:161] offset:32768
	s_cbranch_vccnz .LBB0_828
	global_load_dwordx4 v[146:149], v[190:191], off
	global_load_dwordx4 v[158:161], v[188:189], off

; template <class Toff, class Setup, class Epi>
; DI void gemm256_stream(int tiles_per_xcd, int K, long ais, long akcs, long bis, Toff toff, Setup setup, Epi epi, char* smem) {
;     ...
;   const int nk = K >> 6;
;   __syncthreads();
;   G256_GLOAD(Ac, Bc, 0)
;   G256_SSTORE(0)
;   G256_GLOAD(Ac, Bc, 1)
;   __syncthreads();
;   while (true) {
;     const int qn = q + nj;
;     const bool has_next = qn < tiles_per_xcd;
;     if (has_next) setup(xcd, qn, An, Bn);
;     for (int kt = 0; kt < nk; ++kt) {
;       const int s = kt & 1;
;       const bool have1 = (kt + 1 < nk) || has_next;
;       const bool in_cur = (kt + 2 < nk);
;       const bool have2 = in_cur || (has_next && kt + 2 == nk);
;       const u16* Ap2 = in_cur ? Ac : An;
;       const u16* Bp2 = in_cur ? Bc : Bn;
;       const int kt2 = in_cur ? kt + 2 : kt + 2 - nk;
;       const char* base = smem + s * STAGE;
;       G256_KSTEP(0, ra0, rb0)
;       G256_KSTEP(1, ra1, rb1)
;       G256_KSTEP(2, ra2, rb2)
;       G256_KSTEP(3, ra3, rb3)
;       __syncthreads();
;     }
.LBB0_853:
	s_and_b32 s14, s7, 0x10000
	s_add_i32 s6, s14, 0
	v_add_u32_e32 v0, s6, v195
	v_add3_u32 v174, v0, v218, v219
	v_add3_u32 v0, v0, v220, v219
	s_xor_b32 s14, s14, 0x10000
	s_setprio 1
	ds_read_b128 v[162:165], v174
	ds_read_b128 v[166:169], v174 offset:4096
	ds_read_b128 v[178:181], v174 offset:8192
	ds_read_b128 v[182:185], v174 offset:12288
	ds_read_b128 v[190:193], v0 offset:32768
	ds_read_b128 v[246:249], v0 offset:36864
	v_add_u32_e32 v0, s14, v194
	s_waitcnt vmcnt(7)
	ds_write_b128 v0, v[142:145]
	s_waitcnt vmcnt(6)
	ds_write_b128 v0, v[158:161] offset:32768
	v_lshl_add_u64 v[176:177], v[170:171], 0, s[8:9]
	v_lshl_add_u64 v[174:175], v[172:173], 0, s[8:9]
	global_load_dwordx4 v[142:145], v[176:177], off offset:256
	global_load_dwordx4 v[158:161], v[174:175], off offset:256
	s_waitcnt lgkmcnt(3)
	s_setprio 0
	v_mfma_f32_32x32x16_bf16 v[114:129], v[162:165], v[190:193], v[114:129]
	v_mfma_f32_32x32x16_bf16 v[82:97], v[166:169], v[190:193], v[82:97]
	v_mfma_f32_32x32x16_bf16 v[50:65], v[178:181], v[190:193], v[50:65]
	v_mfma_f32_32x32x16_bf16 v[18:33], v[182:185], v[190:193], v[18:33]
	v_add_u32_e32 v190, s6, v215
	v_add3_u32 v245, v190, v220, v219
	s_waitcnt lgkmcnt(2)
	v_mfma_f32_32x32x16_bf16 v[2:17], v[182:185], v[246:249], v[2:17]
	v_add3_u32 v182, v190, v218, v219
	v_mfma_f32_32x32x16_bf16 v[98:113], v[162:165], v[246:249], v[98:113]
	v_mfma_f32_32x32x16_bf16 v[66:81], v[166:169], v[246:249], v[66:81]
	v_mfma_f32_32x32x16_bf16 v[34:49], v[178:181], v[246:249], v[34:49]
	s_setprio 1
	ds_read_b128 v[162:165], v182
	ds_read_b128 v[166:169], v182 offset:4096
	ds_read_b128 v[178:181], v182 offset:8192
	ds_read_b128 v[182:185], v182 offset:12288
	ds_read_b128 v[190:193], v245 offset:32768
	ds_read_b128 v[246:249], v245 offset:36864
	s_waitcnt vmcnt(7)
	ds_write_b128 v0, v[138:141] offset:8192
	s_waitcnt vmcnt(6)
	ds_write_b128 v0, v[154:157] offset:40960
	v_add_co_u32_e32 v138, vcc, s23, v176
	s_nop 1
	v_addc_co_u32_e32 v139, vcc, 0, v177, vcc
	v_add_co_u32_e32 v154, vcc, s25, v174
	global_load_dwordx4 v[138:141], v[138:139], off offset:256
	s_nop 0
	v_addc_co_u32_e32 v155, vcc, 0, v175, vcc
	global_load_dwordx4 v[154:157], v[154:155], off offset:256
	s_waitcnt lgkmcnt(3)
	s_setprio 0
	v_mfma_f32_32x32x16_bf16 v[114:129], v[162:165], v[190:193], v[114:129]
	v_mfma_f32_32x32x16_bf16 v[82:97], v[166:169], v[190:193], v[82:97]
	v_mfma_f32_32x32x16_bf16 v[50:65], v[178:181], v[190:193], v[50:65]
	v_mfma_f32_32x32x16_bf16 v[18:33], v[182:185], v[190:193], v[18:33]
	v_add_u32_e32 v190, s6, v216
	v_add3_u32 v245, v190, v220, v219
	s_waitcnt lgkmcnt(2)
	v_mfma_f32_32x32x16_bf16 v[2:17], v[182:185], v[246:249], v[2:17]
	v_add3_u32 v182, v190, v218, v219
	v_mfma_f32_32x32x16_bf16 v[98:113], v[162:165], v[246:249], v[98:113]
	v_mfma_f32_32x32x16_bf16 v[66:81], v[166:169], v[246:249], v[66:81]
	v_mfma_f32_32x32x16_bf16 v[34:49], v[178:181], v[246:249], v[34:49]
	s_setprio 1
	ds_read_b128 v[162:165], v182
	ds_read_b128 v[166:169], v182 offset:4096
	ds_read_b128 v[178:181], v182 offset:8192
	ds_read_b128 v[182:185], v182 offset:12288
	ds_read_b128 v[190:193], v245 offset:32768
	ds_read_b128 v[246:249], v245 offset:36864
	s_waitcnt vmcnt(7)
	ds_write_b128 v0, v[134:137] offset:16384
	s_waitcnt vmcnt(6)
	ds_write_b128 v0, v[150:153] offset:49152
	v_add_co_u32_e32 v134, vcc, s22, v176
	s_nop 1
	v_addc_co_u32_e32 v135, vcc, 0, v177, vcc
	v_add_co_u32_e32 v150, vcc, s23, v174
	global_load_dwordx4 v[134:137], v[134:135], off offset:256
	s_nop 0
	v_addc_co_u32_e32 v151, vcc, 0, v175, vcc
	global_load_dwordx4 v[150:153], v[150:151], off offset:256
	s_waitcnt lgkmcnt(3)
	s_setprio 0
	v_mfma_f32_32x32x16_bf16 v[82:97], v[166:169], v[190:193], v[82:97]
	s_waitcnt lgkmcnt(2)
	v_mfma_f32_32x32x16_bf16 v[66:81], v[166:169], v[246:249], v[66:81]
	v_add_u32_e32 v166, s6, v217
	v_mfma_f32_32x32x16_bf16 v[114:129], v[162:165], v[190:193], v[114:129]
	v_mfma_f32_32x32x16_bf16 v[98:113], v[162:165], v[246:249], v[98:113]
	v_add3_u32 v162, v166, v218, v219
	v_add3_u32 v166, v166, v220, v219
	v_mfma_f32_32x32x16_bf16 v[50:65], v[178:181], v[190:193], v[50:65]
	v_mfma_f32_32x32x16_bf16 v[34:49], v[178:181], v[246:249], v[34:49]
	v_mfma_f32_32x32x16_bf16 v[18:33], v[182:185], v[190:193], v[18:33]
	v_mfma_f32_32x32x16_bf16 v[2:17], v[182:185], v[246:249], v[2:17]
	s_setprio 1
	ds_read_b128 v[178:181], v162
	ds_read_b128 v[182:185], v162 offset:4096
	ds_read_b128 v[190:193], v162 offset:8192
	ds_read_b128 v[162:165], v162 offset:12288
	ds_read_b128 v[246:249], v166 offset:32768
	ds_read_b128 v[166:169], v166 offset:36864
	s_waitcnt vmcnt(7)
	ds_write_b128 v0, v[130:133] offset:24576
	s_waitcnt vmcnt(6)
	ds_write_b128 v0, v[146:149] offset:57344
	v_add_co_u32_e32 v130, vcc, s24, v176
	s_nop 1
	v_addc_co_u32_e32 v131, vcc, 0, v177, vcc
	v_add_co_u32_e32 v146, vcc, s26, v174
	global_load_dwordx4 v[130:133], v[130:131], off offset:256
	s_nop 0
	v_addc_co_u32_e32 v147, vcc, 0, v175, vcc
	global_load_dwordx4 v[146:149], v[146:147], off offset:256
	s_waitcnt lgkmcnt(3)
	s_setprio 0
	v_mfma_f32_32x32x16_bf16 v[114:129], v[178:181], v[246:249], v[114:129]
	s_add_u32 s8, s8, 0x80
	s_addc_u32 s9, s9, 0
	s_add_i32 s7, s7, 0x10000
	s_cmpk_eq_i32 s8, 0x700
	s_waitcnt lgkmcnt(0)
	s_barrier
	v_mfma_f32_32x32x16_bf16 v[98:113], v[178:181], v[166:169], v[98:113]
	v_mfma_f32_32x32x16_bf16 v[82:97], v[182:185], v[246:249], v[82:97]
	v_mfma_f32_32x32x16_bf16 v[66:81], v[182:185], v[166:169], v[66:81]
	v_mfma_f32_32x32x16_bf16 v[50:65], v[190:193], v[246:249], v[50:65]
	v_mfma_f32_32x32x16_bf16 v[34:49], v[190:193], v[166:169], v[34:49]
	v_mfma_f32_32x32x16_bf16 v[18:33], v[162:165], v[246:249], v[18:33]
	v_mfma_f32_32x32x16_bf16 v[2:17], v[162:165], v[166:169], v[2:17]
	s_cbranch_scc0 .LBB0_853
	s_setprio 0
	ds_read_b128 v[182:185], v229
	ds_read_b128 v[178:181], v229 offset:4096
	ds_read_b128 v[166:169], v229 offset:8192
	ds_read_b128 v[162:165], v229 offset:12288
	ds_read_b128 v[170:173], v230 offset:32768
	ds_read_b128 v[174:177], v230 offset:36864
	v_cndmask_b32_e64 v0, 0, 1, s[12:13]
	v_cmp_ne_u32_e64 s[8:9], 1, v0
	s_andn2_b64 vcc, exec, s[12:13]
	v_lshl_add_u64 v[190:191], v[188:189], 1, s[10:11]
	v_lshl_add_u64 v[192:193], v[186:187], 1, s[4:5]
	s_waitcnt vmcnt(7)
	ds_write_b128 v221, v[142:145]
	s_waitcnt vmcnt(6)
	ds_write_b128 v222, v[158:161]
	s_cbranch_vccnz .LBB0_856
	global_load_dwordx4 v[142:145], v[192:193], off
	global_load_dwordx4 v[158:161], v[190:191], off
